# v22 + nt hint on the skinny-GEMM (128 sample rows) A/B fragment loads in gateA/gateB/out/up/down
# baseline (speedup 1.0000x reference)
; #define LAS __attribute__((address_space(3)))
; __device__ __forceinline__ f32x4 mfma16(bf16x8 a, bf16x8 b, f32x4 c) { return __builtin_amdgcn_mfma_f32_16x16x32_bf16(a, b, c, 0, 0, 0); }
; __device__ __forceinline__ void sync_threads() { __syncthreads(); }
; template <int RT, class Epi>
; __device__ __forceinline__ void skinny_gemm(const bf16* A, size_t lda, const bf16* Bt, int K, int N, const Epi& epi, int wg, int wg_first, int wg_count, int tid, LAS unsigned char* lds) {
;     ...
;         const bf16* ap = A + (size_t)(r0 + c) * lda + (size_t)w * (K / 8) + 8 * g;
;         const bf16* bp = Bt + (size_t)(n0 + c) * K + (size_t)w * (K / 8) + 8 * g;
; #pragma unroll 4
;         for (int ks = 0; ks < ksteps; ++ks) {
;             bf16x8 af[RT], bfr[2];
; #pragma unroll
;             for (int rt = 0; rt < RT; ++rt) af[rt] = *(const bf16x8*)(ap + (size_t)(16 * rt) * lda + 32 * ks);
;             bfr[0] = *(const bf16x8*)(bp + 32 * ks); bfr[1] = *(const bf16x8*)(bp + (size_t)16 * K + 32 * ks);
; #pragma unroll
;             for (int rt = 0; rt < RT; ++rt) { acc[rt][0] = mfma16(af[rt], bfr[0], acc[rt][0]); acc[rt][1] = mfma16(af[rt], bfr[1], acc[rt][1]); }
;         }
;         LAS float* part = (LAS float*)(lds + w * SK_PART);
; #pragma unroll
;         for (int rt = 0; rt < RT; ++rt)
; #pragma unroll
;             for (int nt = 0; nt < 2; ++nt)
; #pragma unroll
;                 for (int r = 0; r < 4; ++r) part[(16 * rt + 4 * g + r) * 32 + 16 * nt + c] = acc[rt][nt][r];
;         sync_threads();
;         if (RT == 8 || tid < 64 * RT) {
;             const int row = tid >> 2, c8 = (tid & 3) * 8;
;             f32x4 v0 = (f32x4){0.f, 0.f, 0.f, 0.f}, v1 = (f32x4){0.f, 0.f, 0.f, 0.f};
; #pragma unroll
;             for (int ww = 0; ww < 8; ++ww) { const LAS float* pp = (const LAS float*)(lds + ww * SK_PART) + row * 32 + c8; v0 = v0 + *(const LAS f32x4*)pp; v1 = v1 + *(const LAS f32x4*)(pp + 4); }
;             epi(r0 + row, n0 + c8, v0, v1);
.LBB0_987:
	s_and_b32 s16, s13, 0x70
	v_or_b32_e32 v0, s16, v26
	s_and_b32 s15, s12, 0x7fffffe0
	v_lshlrev_b32_e32 v10, 11, v0
	v_lshl_add_u64 v[40:41], v[8:9], 0, v[10:11]
	v_or_b32_e32 v10, s15, v26
	v_lshlrev_b64 v[0:1], 11, v[10:11]
	v_lshl_add_u64 v[42:43], v[12:13], 0, v[0:1]
	v_add_co_u32_e32 v44, vcc, 0x8000, v42
	global_load_dwordx4 v[0:3], v[40:41], off nt
	global_load_dwordx4 v[4:7], v[42:43], off nt
	v_addc_co_u32_e32 v45, vcc, 0, v43, vcc
	global_load_dwordx4 v[14:17], v[44:45], off nt
	s_waitcnt vmcnt(0) lgkmcnt(0)
	v_mfma_f32_16x16x32_bf16 v[4:7], v[0:3], v[4:7], 0
	v_mfma_f32_16x16x32_bf16 v[0:3], v[0:3], v[14:17], 0
	global_load_dwordx4 v[14:17], v[40:41], off offset:64 nt
	global_load_dwordx4 v[18:21], v[42:43], off offset:64 nt
	global_load_dwordx4 v[22:25], v[44:45], off offset:64 nt
	s_waitcnt vmcnt(0) lgkmcnt(0)
	v_mfma_f32_16x16x32_bf16 v[4:7], v[14:17], v[18:21], v[4:7]
	v_mfma_f32_16x16x32_bf16 v[0:3], v[14:17], v[22:25], v[0:3]
	global_load_dwordx4 v[14:17], v[40:41], off offset:128 nt
	global_load_dwordx4 v[18:21], v[42:43], off offset:128 nt
	global_load_dwordx4 v[22:25], v[44:45], off offset:128 nt
	s_waitcnt vmcnt(0) lgkmcnt(0)
	v_mfma_f32_16x16x32_bf16 v[4:7], v[14:17], v[18:21], v[4:7]
	v_mfma_f32_16x16x32_bf16 v[0:3], v[14:17], v[22:25], v[0:3]
	global_load_dwordx4 v[14:17], v[40:41], off offset:192 nt
	global_load_dwordx4 v[18:21], v[42:43], off offset:192 nt
	global_load_dwordx4 v[22:25], v[44:45], off offset:192 nt
	s_waitcnt vmcnt(0) lgkmcnt(0)
	v_mfma_f32_16x16x32_bf16 v[4:7], v[14:17], v[18:21], v[4:7]
	v_mfma_f32_16x16x32_bf16 v[0:3], v[14:17], v[22:25], v[0:3]
	s_nop 7
	ds_write2_b32 v38, v4, v0 offset1:16
	ds_write2_b32 v38, v5, v1 offset0:32 offset1:48
	ds_write2_b32 v38, v6, v2 offset0:64 offset1:80
	ds_write2_b32 v38, v7, v3 offset0:96 offset1:112
	s_waitcnt lgkmcnt(0)
	s_barrier
	s_and_saveexec_b64 s[2:3], s[6:7]
	s_cbranch_execz .LBB0_986
	ds_read_b128 v[0:3], v29
	ds_read_b128 v[4:7], v29 offset:16
	v_add_u32_e32 v20, s16, v27
	v_or_b32_e32 v10, s15, v28
	v_lshlrev_b32_e32 v24, 1, v10
	s_waitcnt lgkmcnt(1)
	v_pk_add_f32 v[14:15], v[2:3], 0 op_sel_hi:[1,0]
	v_pk_add_f32 v[16:17], v[0:1], 0 op_sel_hi:[1,0]
	ds_read_b128 v[0:3], v29 offset:16384
	s_waitcnt lgkmcnt(1)
	v_pk_add_f32 v[6:7], v[6:7], 0 op_sel_hi:[1,0]
	v_pk_add_f32 v[4:5], v[4:5], 0 op_sel_hi:[1,0]
	v_mov_b32_e32 v25, v11
	v_ashrrev_i32_e32 v21, 31, v20
	s_waitcnt lgkmcnt(0)
	v_pk_add_f32 v[14:15], v[14:15], v[2:3]
	v_pk_add_f32 v[16:17], v[16:17], v[0:1]
	ds_read_b128 v[0:3], v29 offset:16400
	s_waitcnt lgkmcnt(0)
	v_pk_add_f32 v[6:7], v[6:7], v[2:3]
	v_pk_add_f32 v[4:5], v[4:5], v[0:1]
	ds_read_b128 v[0:3], v29 offset:32768
	s_waitcnt lgkmcnt(0)
	v_pk_add_f32 v[14:15], v[14:15], v[2:3]
	v_pk_add_f32 v[16:17], v[16:17], v[0:1]
	ds_read_b128 v[0:3], v29 offset:32784
	s_waitcnt lgkmcnt(0)
	v_pk_add_f32 v[6:7], v[6:7], v[2:3]
	v_pk_add_f32 v[4:5], v[4:5], v[0:1]
	ds_read_b128 v[0:3], v29 offset:49152
	s_waitcnt lgkmcnt(0)
	v_pk_add_f32 v[14:15], v[14:15], v[2:3]
	v_pk_add_f32 v[16:17], v[16:17], v[0:1]
	ds_read_b128 v[0:3], v29 offset:49168
	s_waitcnt lgkmcnt(0)
	v_pk_add_f32 v[6:7], v[6:7], v[2:3]
	v_pk_add_f32 v[4:5], v[4:5], v[0:1]
	ds_read_b128 v[0:3], v30
	s_waitcnt lgkmcnt(0)
	v_pk_add_f32 v[14:15], v[14:15], v[2:3]
	v_pk_add_f32 v[16:17], v[16:17], v[0:1]
	ds_read_b128 v[0:3], v31
	s_waitcnt lgkmcnt(0)
	v_pk_add_f32 v[6:7], v[6:7], v[2:3]
	v_pk_add_f32 v[4:5], v[4:5], v[0:1]
	ds_read_b128 v[0:3], v32
	s_waitcnt lgkmcnt(0)
	v_pk_add_f32 v[14:15], v[14:15], v[2:3]
	v_pk_add_f32 v[16:17], v[16:17], v[0:1]
	ds_read_b128 v[0:3], v33
	s_waitcnt lgkmcnt(0)
	v_pk_add_f32 v[6:7], v[6:7], v[2:3]
	v_pk_add_f32 v[4:5], v[4:5], v[0:1]
	ds_read_b128 v[0:3], v34
	s_waitcnt lgkmcnt(0)
	v_pk_add_f32 v[14:15], v[14:15], v[2:3]
	v_pk_add_f32 v[18:19], v[16:17], v[0:1]
	ds_read_b128 v[0:3], v35
	s_waitcnt lgkmcnt(0)
	v_pk_add_f32 v[6:7], v[6:7], v[2:3]
	v_pk_add_f32 v[4:5], v[4:5], v[0:1]
	ds_read_b128 v[0:3], v36
	s_waitcnt lgkmcnt(0)
	v_pk_add_f32 v[16:17], v[14:15], v[2:3]
	v_pk_add_f32 v[22:23], v[18:19], v[0:1]
	ds_read_b128 v[0:3], v37
	s_waitcnt lgkmcnt(0)
	v_pk_add_f32 v[18:19], v[4:5], v[0:1]
	v_mov_b64_e32 v[0:1], s[10:11]
	v_mad_i64_i32 v[0:1], s[16:17], v20, s77, v[0:1]
	v_lshl_add_u64 v[0:1], v[0:1], 0, v[24:25]
	v_pk_add_f32 v[14:15], v[6:7], v[2:3]
	global_load_dwordx4 v[0:3], v[0:1], off nt
	v_lshl_add_u64 v[4:5], v[10:11], 2, s[0:1]
	s_waitcnt vmcnt(0) lgkmcnt(0)
	v_lshlrev_b32_e32 v41, 16, v0
	v_and_b32_e32 v42, 0xffff0000, v0
	v_lshlrev_b32_e32 v43, 16, v1
	v_and_b32_e32 v40, 0xffff0000, v1
	v_lshlrev_b32_e32 v44, 16, v2
	v_and_b32_e32 v45, 0xffff0000, v2
	v_lshlrev_b32_e32 v46, 16, v3
	v_and_b32_e32 v39, 0xffff0000, v3
	global_load_dwordx4 v[0:3], v[4:5], off offset:16 nt
	s_nop 0
	global_load_dwordx4 v[4:7], v[4:5], off nt
	s_waitcnt vmcnt(1)
	v_add_f32_e32 v0, v0, v44
	v_add_f32_e32 v1, v1, v45
	v_add_f32_e32 v2, v2, v46
	v_mul_f32_e32 v0, 0xbfb8aa3b, v0
	v_mul_f32_e32 v1, 0xbfb8aa3b, v1
	v_mul_f32_e32 v2, 0xbfb8aa3b, v2
	v_exp_f32_e32 v0, v0
	v_exp_f32_e32 v1, v1
	v_exp_f32_e32 v2, v2
	s_waitcnt vmcnt(0)
	v_add_f32_e32 v4, v4, v41
	v_add_f32_e32 v0, 1.0, v0
	v_add_f32_e32 v1, 1.0, v1
	v_add_f32_e32 v2, 1.0, v2
	v_rcp_f32_e32 v0, v0
	v_rcp_f32_e32 v1, v1
	v_rcp_f32_e32 v2, v2
	v_mul_f32_e32 v4, 0xbfb8aa3b, v4
	v_mul_f32_e32 v10, v18, v0
	v_add_f32_e32 v0, v5, v42
	v_mul_f32_e32 v5, v19, v1
	v_add_f32_e32 v1, v6, v43
	v_mul_f32_e32 v6, v14, v2
	v_add_f32_e32 v2, v7, v40
	v_mul_f32_e32 v0, 0xbfb8aa3b, v0
	v_mul_f32_e32 v1, 0xbfb8aa3b, v1
	v_mul_f32_e32 v2, 0xbfb8aa3b, v2
	v_exp_f32_e32 v4, v4
	v_exp_f32_e32 v0, v0
	v_exp_f32_e32 v1, v1
	v_exp_f32_e32 v2, v2
	v_add_f32_e32 v3, v3, v39
	v_mul_f32_e32 v3, 0xbfb8aa3b, v3
	v_exp_f32_e32 v3, v3
	v_add_f32_e32 v4, 1.0, v4
	v_add_f32_e32 v0, 1.0, v0
	v_add_f32_e32 v1, 1.0, v1
	v_add_f32_e32 v2, 1.0, v2
	v_rcp_f32_e32 v4, v4
	v_rcp_f32_e32 v0, v0
	v_rcp_f32_e32 v1, v1
	v_rcp_f32_e32 v2, v2
	v_add_f32_e32 v3, 1.0, v3
	v_rcp_f32_e32 v3, v3
	v_mul_f32_e32 v4, v22, v4
	v_mul_f32_e32 v0, v23, v0
	v_mul_f32_e32 v1, v16, v1
	v_mul_f32_e32 v2, v17, v2
	v_cvt_pk_bf16_f32 v0, v4, v0
	v_cvt_pk_bf16_f32 v1, v1, v2
	v_cvt_pk_bf16_f32 v2, v10, v5
	v_lshlrev_b64 v[4:5], 11, v[20:21]
	v_lshl_add_u64 v[4:5], s[8:9], 0, v[4:5]
	v_mul_f32_e32 v3, v15, v3
	v_lshl_add_u64 v[4:5], v[4:5], 0, v[24:25]
	v_cvt_pk_bf16_f32 v3, v6, v3
	global_store_dwordx4 v[4:5], v[0:3], off
	s_branch .LBB0_986

; __device__ __forceinline__ f32x4 mfma16(bf16x8 a, bf16x8 b, f32x4 c) { return __builtin_amdgcn_mfma_f32_16x16x32_bf16(a, b, c, 0, 0, 0); }
; template <int RT, class Epi>
; __device__ __forceinline__ void skinny_gemm(const bf16* A, size_t lda, const bf16* Bt, int K, int N, const Epi& epi, int wg, int wg_first, int wg_count, int tid, LAS unsigned char* lds) {
;     ...
;         const bf16* ap = A + (size_t)(r0 + c) * lda + (size_t)w * (K / 8) + 8 * g;
;         const bf16* bp = Bt + (size_t)(n0 + c) * K + (size_t)w * (K / 8) + 8 * g;
; #pragma unroll 4
;         for (int ks = 0; ks < ksteps; ++ks) {
;             bf16x8 af[RT], bfr[2];
; #pragma unroll
;             for (int rt = 0; rt < RT; ++rt) af[rt] = *(const bf16x8*)(ap + (size_t)(16 * rt) * lda + 32 * ks);
;             bfr[0] = *(const bf16x8*)(bp + 32 * ks); bfr[1] = *(const bf16x8*)(bp + (size_t)16 * K + 32 * ks);
; #pragma unroll
;             for (int rt = 0; rt < RT; ++rt) { acc[rt][0] = mfma16(af[rt], bfr[0], acc[rt][0]); acc[rt][1] = mfma16(af[rt], bfr[1], acc[rt][1]); }
;         }
.LBB0_1013:
	v_lshl_add_u64 v[18:19], v[14:15], 0, s[8:9]
	v_add_co_u32_e32 v44, vcc, 0x36600000, v18
	v_lshl_add_u64 v[40:41], v[16:17], 0, s[8:9]
	s_nop 0
	v_addc_co_u32_e32 v45, vcc, 0, v19, vcc
	global_load_dwordx4 v[18:21], v[44:45], off nt
	v_add_co_u32_e32 v46, vcc, 0x6a80000, v40
	s_add_u32 s8, s8, 0x100
	s_nop 0
	v_addc_co_u32_e32 v47, vcc, 0, v41, vcc
	v_add_co_u32_e32 v48, vcc, 0x6a90000, v40
	global_load_dwordx4 v[22:25], v[46:47], off nt
	s_nop 0
	v_addc_co_u32_e32 v49, vcc, 0, v41, vcc
	global_load_dwordx4 v[40:43], v[48:49], off nt
	s_addc_u32 s9, s9, 0
	s_cmpk_eq_i32 s8, 0x200
	s_waitcnt vmcnt(0) lgkmcnt(0)
	v_mfma_f32_16x16x32_bf16 v[0:3], v[18:21], v[22:25], v[0:3]
	v_mfma_f32_16x16x32_bf16 v[4:7], v[18:21], v[40:43], v[4:7]
	global_load_dwordx4 v[18:21], v[44:45], off offset:64 nt
	global_load_dwordx4 v[22:25], v[46:47], off offset:64 nt
	global_load_dwordx4 v[40:43], v[48:49], off offset:64 nt
	s_waitcnt vmcnt(0) lgkmcnt(0)
	v_mfma_f32_16x16x32_bf16 v[0:3], v[18:21], v[22:25], v[0:3]
	v_mfma_f32_16x16x32_bf16 v[4:7], v[18:21], v[40:43], v[4:7]
	global_load_dwordx4 v[18:21], v[44:45], off offset:128 nt
	global_load_dwordx4 v[22:25], v[46:47], off offset:128 nt
	global_load_dwordx4 v[40:43], v[48:49], off offset:128 nt
	s_waitcnt vmcnt(0) lgkmcnt(0)
	v_mfma_f32_16x16x32_bf16 v[0:3], v[18:21], v[22:25], v[0:3]
	v_mfma_f32_16x16x32_bf16 v[4:7], v[18:21], v[40:43], v[4:7]
	global_load_dwordx4 v[18:21], v[44:45], off offset:192 nt
	global_load_dwordx4 v[22:25], v[46:47], off offset:192 nt
	global_load_dwordx4 v[40:43], v[48:49], off offset:192 nt
	s_waitcnt vmcnt(0) lgkmcnt(0)
	v_mfma_f32_16x16x32_bf16 v[0:3], v[18:21], v[22:25], v[0:3]
	v_mfma_f32_16x16x32_bf16 v[4:7], v[18:21], v[40:43], v[4:7]
	s_cbranch_scc0 .LBB0_1013
	s_nop 6
	ds_write2_b32 v39, v0, v4 offset1:16
	ds_write2_b32 v39, v1, v5 offset0:32 offset1:48
	ds_write2_b32 v39, v2, v6 offset0:64 offset1:80
	ds_write2_b32 v39, v3, v7 offset0:96 offset1:112
	s_waitcnt lgkmcnt(0)
	s_barrier
	s_and_saveexec_b64 s[8:9], s[6:7]
	s_cbranch_execz .LBB0_1011
; #define LAS __attribute__((address_space(3)))
; __device__ __forceinline__ void sync_threads() { __syncthreads(); }
; template <int RT, class Epi>
; __device__ __forceinline__ void skinny_gemm(const bf16* A, size_t lda, const bf16* Bt, int K, int N, const Epi& epi, int wg, int wg_first, int wg_count, int tid, LAS unsigned char* lds) {
;     ...
;         LAS float* part = (LAS float*)(lds + w * SK_PART);
; #pragma unroll
;         for (int rt = 0; rt < RT; ++rt)
; #pragma unroll
;             for (int nt = 0; nt < 2; ++nt)
; #pragma unroll
;                 for (int r = 0; r < 4; ++r) part[(16 * rt + 4 * g + r) * 32 + 16 * nt + c] = acc[rt][nt][r];
;         sync_threads();
;         if (RT == 8 || tid < 64 * RT) {
;             const int row = tid >> 2, c8 = (tid & 3) * 8;
;             f32x4 v0 = (f32x4){0.f, 0.f, 0.f, 0.f}, v1 = (f32x4){0.f, 0.f, 0.f, 0.f};
; #pragma unroll
;             for (int ww = 0; ww < 8; ++ww) { const LAS float* pp = (const LAS float*)(lds + ww * SK_PART) + row * 32 + c8; v0 = v0 + *(const LAS f32x4*)pp; v1 = v1 + *(const LAS f32x4*)(pp + 4); }
;             epi(r0 + row, n0 + c8, v0, v1);
;         }
	ds_read_b128 v[0:3], v29
	ds_read_b128 v[4:7], v29 offset:16
	s_lshl_b32 s17, s16, 2
	s_lshl_b32 s18, s16, 4
	s_and_b32 s17, s17, 0x7fffffe0
	s_waitcnt lgkmcnt(1)
	v_pk_add_f32 v[14:15], v[2:3], 0 op_sel_hi:[1,0]
	v_pk_add_f32 v[16:17], v[0:1], 0 op_sel_hi:[1,0]
	ds_read_b128 v[0:3], v29 offset:16384
	s_waitcnt lgkmcnt(1)
	v_pk_add_f32 v[6:7], v[6:7], 0 op_sel_hi:[1,0]
	v_pk_add_f32 v[4:5], v[4:5], 0 op_sel_hi:[1,0]
	s_and_b32 s18, s18, 0x70
	v_add_u32_e32 v24, s18, v27
	s_waitcnt lgkmcnt(0)
	v_pk_add_f32 v[14:15], v[14:15], v[2:3]
	v_pk_add_f32 v[16:17], v[16:17], v[0:1]
	ds_read_b128 v[0:3], v29 offset:16400
	v_or_b32_e32 v10, s17, v28
	v_lshlrev_b32_e32 v22, 1, v10
	v_mov_b32_e32 v23, v11
	v_ashrrev_i32_e32 v25, 31, v24
	s_waitcnt lgkmcnt(0)
	v_pk_add_f32 v[6:7], v[6:7], v[2:3]
	v_pk_add_f32 v[4:5], v[4:5], v[0:1]
	ds_read_b128 v[0:3], v29 offset:32768
	s_waitcnt lgkmcnt(0)
	v_pk_add_f32 v[14:15], v[14:15], v[2:3]
	v_pk_add_f32 v[16:17], v[16:17], v[0:1]
	ds_read_b128 v[0:3], v29 offset:32784
	s_waitcnt lgkmcnt(0)
	v_pk_add_f32 v[6:7], v[6:7], v[2:3]
	v_pk_add_f32 v[4:5], v[4:5], v[0:1]
	ds_read_b128 v[0:3], v29 offset:49152
	s_waitcnt lgkmcnt(0)
	v_pk_add_f32 v[14:15], v[14:15], v[2:3]
	v_pk_add_f32 v[16:17], v[16:17], v[0:1]
	ds_read_b128 v[0:3], v29 offset:49168
	s_waitcnt lgkmcnt(0)
	v_pk_add_f32 v[6:7], v[6:7], v[2:3]
	v_pk_add_f32 v[4:5], v[4:5], v[0:1]
	ds_read_b128 v[0:3], v30
	s_waitcnt lgkmcnt(0)
	v_pk_add_f32 v[14:15], v[14:15], v[2:3]
	v_pk_add_f32 v[16:17], v[16:17], v[0:1]
	ds_read_b128 v[0:3], v31
	s_waitcnt lgkmcnt(0)
	v_pk_add_f32 v[6:7], v[6:7], v[2:3]
	v_pk_add_f32 v[4:5], v[4:5], v[0:1]
	ds_read_b128 v[0:3], v32
	s_waitcnt lgkmcnt(0)
	v_pk_add_f32 v[14:15], v[14:15], v[2:3]
	v_pk_add_f32 v[16:17], v[16:17], v[0:1]
	ds_read_b128 v[0:3], v33
	s_waitcnt lgkmcnt(0)
	v_pk_add_f32 v[6:7], v[6:7], v[2:3]
	v_pk_add_f32 v[4:5], v[4:5], v[0:1]
	ds_read_b128 v[0:3], v34
	s_waitcnt lgkmcnt(0)
	v_pk_add_f32 v[14:15], v[14:15], v[2:3]
	v_pk_add_f32 v[18:19], v[16:17], v[0:1]
	ds_read_b128 v[0:3], v35
	s_waitcnt lgkmcnt(0)
	v_pk_add_f32 v[6:7], v[6:7], v[2:3]
	v_pk_add_f32 v[4:5], v[4:5], v[0:1]
	ds_read_b128 v[0:3], v36
	s_waitcnt lgkmcnt(0)
	v_pk_add_f32 v[16:17], v[14:15], v[2:3]
	v_pk_add_f32 v[20:21], v[18:19], v[0:1]
	ds_read_b128 v[0:3], v37
	s_waitcnt lgkmcnt(0)
	v_pk_add_f32 v[18:19], v[4:5], v[0:1]
	v_mov_b64_e32 v[0:1], s[12:13]
	v_mad_i64_i32 v[0:1], s[18:19], v24, s77, v[0:1]
	v_lshl_add_u64 v[0:1], v[0:1], 0, v[22:23]
	v_pk_add_f32 v[14:15], v[6:7], v[2:3]
	global_load_dwordx4 v[0:3], v[0:1], off nt
	v_lshl_add_u64 v[4:5], v[10:11], 2, s[0:1]
	v_lshlrev_b64 v[24:25], 11, v[24:25]
	v_lshl_add_u64 v[42:43], s[2:3], 0, v[24:25]
	v_lshl_add_u64 v[42:43], v[42:43], 0, v[22:23]
	s_waitcnt vmcnt(0) lgkmcnt(0)
	v_lshlrev_b32_e32 v50, 16, v0
	v_and_b32_e32 v51, 0xffff0000, v0
	v_lshlrev_b32_e32 v52, 16, v1
	v_and_b32_e32 v45, 0xffff0000, v1
	v_lshlrev_b32_e32 v53, 16, v2
	v_and_b32_e32 v54, 0xffff0000, v2
	v_lshlrev_b32_e32 v55, 16, v3
	v_and_b32_e32 v40, 0xffff0000, v3
	global_load_dwordx4 v[0:3], v[4:5], off offset:16 nt
	s_nop 0
	global_load_dwordx4 v[4:7], v[4:5], off nt
	s_waitcnt vmcnt(1)
	v_add_f32_e32 v0, v0, v53
	global_load_dwordx4 v[46:49], v[42:43], off nt
	v_mul_f32_e32 v0, 0xbfb8aa3b, v0
	v_exp_f32_e32 v0, v0
	s_waitcnt vmcnt(0)
	v_add_f32_e32 v4, v4, v50
	v_mul_f32_e32 v4, 0xbfb8aa3b, v4
	v_exp_f32_e32 v4, v4
	v_add_f32_e32 v0, 1.0, v0
	v_rcp_f32_e32 v0, v0
	v_add_f32_e32 v4, 1.0, v4
	v_rcp_f32_e32 v4, v4
	s_waitcnt lgkmcnt(0)
	v_lshlrev_b32_e32 v44, 16, v48
	v_fmac_f32_e32 v44, v18, v0
	v_add_f32_e32 v0, v5, v51
	v_mul_f32_e32 v0, 0xbfb8aa3b, v0
	v_exp_f32_e32 v0, v0
	v_and_b32_e32 v41, 0xffff0000, v46
	v_lshlrev_b32_e32 v10, 16, v46
	v_and_b32_e32 v46, 0xffff0000, v48
	v_add_f32_e32 v0, 1.0, v0
	v_rcp_f32_e32 v0, v0
	v_lshlrev_b32_e32 v42, 16, v47
	v_and_b32_e32 v43, 0xffff0000, v47
	v_lshlrev_b32_e32 v47, 16, v49
	v_fmac_f32_e32 v41, v21, v0
	v_add_f32_e32 v0, v1, v54
	v_mul_f32_e32 v0, 0xbfb8aa3b, v0
	v_exp_f32_e32 v0, v0
	v_fmac_f32_e32 v10, v20, v4
	v_lshl_add_u64 v[4:5], s[10:11], 0, v[24:25]
	v_and_b32_e32 v48, 0xffff0000, v49
	v_add_f32_e32 v0, 1.0, v0
	v_rcp_f32_e32 v0, v0
	v_lshl_add_u64 v[4:5], v[4:5], 0, v[22:23]
	v_fmac_f32_e32 v46, v19, v0
	v_add_f32_e32 v0, v6, v52
	v_mul_f32_e32 v0, 0xbfb8aa3b, v0
	v_exp_f32_e32 v0, v0
	s_nop 0
	v_add_f32_e32 v0, 1.0, v0
	v_rcp_f32_e32 v0, v0
	s_nop 0
	v_fmac_f32_e32 v42, v16, v0
	v_add_f32_e32 v0, v2, v55
	v_mul_f32_e32 v0, 0xbfb8aa3b, v0
	v_exp_f32_e32 v0, v0
	v_cvt_pk_bf16_f32 v2, v44, v46
	s_nop 0
	v_add_f32_e32 v0, 1.0, v0
	v_rcp_f32_e32 v0, v0
	s_nop 0
	v_fmac_f32_e32 v47, v14, v0
	v_add_f32_e32 v0, v7, v45
	v_mul_f32_e32 v0, 0xbfb8aa3b, v0
	v_exp_f32_e32 v0, v0
	s_nop 0
	v_add_f32_e32 v0, 1.0, v0
	v_rcp_f32_e32 v0, v0
	s_nop 0
	v_fmac_f32_e32 v43, v17, v0
	v_add_f32_e32 v0, v3, v40
	v_mul_f32_e32 v0, 0xbfb8aa3b, v0
	v_exp_f32_e32 v0, v0
	v_cvt_pk_bf16_f32 v1, v42, v43
	s_nop 0
	v_add_f32_e32 v0, 1.0, v0
	v_rcp_f32_e32 v0, v0
	s_nop 0
	v_fmac_f32_e32 v48, v15, v0
	v_cvt_pk_bf16_f32 v0, v10, v41
	v_cvt_pk_bf16_f32 v3, v47, v48
	global_store_dwordx4 v[4:5], v[0:3], off
	s_branch .LBB0_1011

; #define LAS __attribute__((address_space(3)))
; __device__ __forceinline__ f32x4 mfma16(bf16x8 a, bf16x8 b, f32x4 c) { return __builtin_amdgcn_mfma_f32_16x16x32_bf16(a, b, c, 0, 0, 0); }
; __device__ __forceinline__ void sync_threads() { __syncthreads(); }
; template <int RT, class Epi>
; __device__ __forceinline__ void skinny_gemm(const bf16* A, size_t lda, const bf16* Bt, int K, int N, const Epi& epi, int wg, int wg_first, int wg_count, int tid, LAS unsigned char* lds) {
;     ...
;         const bf16* ap = A + (size_t)(r0 + c) * lda + (size_t)w * (K / 8) + 8 * g;
;         const bf16* bp = Bt + (size_t)(n0 + c) * K + (size_t)w * (K / 8) + 8 * g;
; #pragma unroll 4
;         for (int ks = 0; ks < ksteps; ++ks) {
;             bf16x8 af[RT], bfr[2];
; #pragma unroll
;             for (int rt = 0; rt < RT; ++rt) af[rt] = *(const bf16x8*)(ap + (size_t)(16 * rt) * lda + 32 * ks);
;             bfr[0] = *(const bf16x8*)(bp + 32 * ks); bfr[1] = *(const bf16x8*)(bp + (size_t)16 * K + 32 * ks);
; #pragma unroll
;             for (int rt = 0; rt < RT; ++rt) { acc[rt][0] = mfma16(af[rt], bfr[0], acc[rt][0]); acc[rt][1] = mfma16(af[rt], bfr[1], acc[rt][1]); }
;         }
;         LAS float* part = (LAS float*)(lds + w * SK_PART);
; #pragma unroll
;         for (int rt = 0; rt < RT; ++rt)
; #pragma unroll
;             for (int nt = 0; nt < 2; ++nt)
; #pragma unroll
;                 for (int r = 0; r < 4; ++r) part[(16 * rt + 4 * g + r) * 32 + 16 * nt + c] = acc[rt][nt][r];
;         sync_threads();
;         if (RT == 8 || tid < 64 * RT) {
;             const int row = tid >> 2, c8 = (tid & 3) * 8;
;             f32x4 v0 = (f32x4){0.f, 0.f, 0.f, 0.f}, v1 = (f32x4){0.f, 0.f, 0.f, 0.f};
; #pragma unroll
;             for (int ww = 0; ww < 8; ++ww) { const LAS float* pp = (const LAS float*)(lds + ww * SK_PART) + row * 32 + c8; v0 = v0 + *(const LAS f32x4*)pp; v1 = v1 + *(const LAS f32x4*)(pp + 4); }
;             epi(r0 + row, n0 + c8, v0, v1);
;         }
.LBB0_1084:
	s_and_b32 s16, s9, 0x70
	v_or_b32_e32 v4, s16, v20
	s_and_b32 s15, s8, 0x7fffffe0
	v_lshlrev_b32_e32 v10, 11, v4
	v_lshl_add_u64 v[8:9], v[0:1], 0, v[10:11]
	v_or_b32_e32 v10, s15, v20
	v_lshlrev_b64 v[4:5], 11, v[10:11]
	v_lshl_add_u64 v[42:43], v[2:3], 0, v[4:5]
	v_add_co_u32_e32 v44, vcc, 0x8000, v42
	global_load_dwordx4 v[4:7], v[8:9], off nt
	global_load_dwordx4 v[12:15], v[42:43], off nt
	v_addc_co_u32_e32 v45, vcc, 0, v43, vcc
	global_load_dwordx4 v[16:19], v[44:45], off nt
	s_waitcnt vmcnt(0) lgkmcnt(0)
	v_mfma_f32_16x16x32_bf16 v[12:15], v[4:7], v[12:15], 0
	v_mfma_f32_16x16x32_bf16 v[4:7], v[4:7], v[16:19], 0
	global_load_dwordx4 v[16:19], v[8:9], off offset:64 nt
	global_load_dwordx4 v[34:37], v[42:43], off offset:64 nt
	global_load_dwordx4 v[38:41], v[44:45], off offset:64 nt
	s_waitcnt vmcnt(0) lgkmcnt(0)
	v_mfma_f32_16x16x32_bf16 v[12:15], v[16:19], v[34:37], v[12:15]
	v_mfma_f32_16x16x32_bf16 v[4:7], v[16:19], v[38:41], v[4:7]
	global_load_dwordx4 v[16:19], v[8:9], off offset:128 nt
	global_load_dwordx4 v[34:37], v[42:43], off offset:128 nt
	global_load_dwordx4 v[38:41], v[44:45], off offset:128 nt
	s_waitcnt vmcnt(0) lgkmcnt(0)
	v_mfma_f32_16x16x32_bf16 v[12:15], v[16:19], v[34:37], v[12:15]
	v_mfma_f32_16x16x32_bf16 v[4:7], v[16:19], v[38:41], v[4:7]
	global_load_dwordx4 v[16:19], v[8:9], off offset:192 nt
	global_load_dwordx4 v[34:37], v[42:43], off offset:192 nt
	global_load_dwordx4 v[38:41], v[44:45], off offset:192 nt
	s_waitcnt vmcnt(0) lgkmcnt(0)
	v_mfma_f32_16x16x32_bf16 v[12:15], v[16:19], v[34:37], v[12:15]
	v_mfma_f32_16x16x32_bf16 v[4:7], v[16:19], v[38:41], v[4:7]
	s_nop 7
	ds_write2_b32 v32, v12, v4 offset1:16
	ds_write2_b32 v32, v13, v5 offset0:32 offset1:48
	ds_write2_b32 v32, v14, v6 offset0:64 offset1:80
	ds_write2_b32 v32, v15, v7 offset0:96 offset1:112
	s_waitcnt lgkmcnt(0)
	s_barrier
	s_and_saveexec_b64 s[2:3], s[6:7]
	s_cbranch_execz .LBB0_1083
	ds_read_b128 v[4:7], v23
	ds_read_b128 v[12:15], v23 offset:16
	v_or_b32_e32 v10, s15, v22
	s_mov_b32 s15, 0x18000
	s_waitcnt lgkmcnt(1)
	v_pk_add_f32 v[8:9], v[6:7], 0 op_sel_hi:[1,0]
	v_pk_add_f32 v[16:17], v[4:5], 0 op_sel_hi:[1,0]
	ds_read_b128 v[4:7], v23 offset:16384
	s_waitcnt lgkmcnt(1)
	v_pk_add_f32 v[14:15], v[14:15], 0 op_sel_hi:[1,0]
	v_pk_add_f32 v[12:13], v[12:13], 0 op_sel_hi:[1,0]
	s_waitcnt lgkmcnt(0)
	v_pk_add_f32 v[8:9], v[8:9], v[6:7]
	v_pk_add_f32 v[16:17], v[16:17], v[4:5]
	ds_read_b128 v[4:7], v23 offset:16400
	s_waitcnt lgkmcnt(0)
	v_pk_add_f32 v[14:15], v[14:15], v[6:7]
	v_pk_add_f32 v[12:13], v[12:13], v[4:5]
	ds_read_b128 v[4:7], v23 offset:32768
	s_waitcnt lgkmcnt(0)
	v_pk_add_f32 v[8:9], v[8:9], v[6:7]
	v_pk_add_f32 v[16:17], v[16:17], v[4:5]
	ds_read_b128 v[4:7], v23 offset:32784
	s_waitcnt lgkmcnt(0)
	v_pk_add_f32 v[14:15], v[14:15], v[6:7]
	v_pk_add_f32 v[12:13], v[12:13], v[4:5]
	ds_read_b128 v[4:7], v23 offset:49152
	s_waitcnt lgkmcnt(0)
	v_pk_add_f32 v[8:9], v[8:9], v[6:7]
	v_pk_add_f32 v[16:17], v[16:17], v[4:5]
	ds_read_b128 v[4:7], v23 offset:49168
	s_waitcnt lgkmcnt(0)
	v_pk_add_f32 v[14:15], v[14:15], v[6:7]
	v_pk_add_f32 v[12:13], v[12:13], v[4:5]
	ds_read_b128 v[4:7], v24
	s_waitcnt lgkmcnt(0)
	v_pk_add_f32 v[8:9], v[8:9], v[6:7]
	v_pk_add_f32 v[16:17], v[16:17], v[4:5]
	ds_read_b128 v[4:7], v25
	s_waitcnt lgkmcnt(0)
	v_pk_add_f32 v[14:15], v[14:15], v[6:7]
	v_pk_add_f32 v[12:13], v[12:13], v[4:5]
	ds_read_b128 v[4:7], v26
	s_waitcnt lgkmcnt(0)
	v_pk_add_f32 v[8:9], v[8:9], v[6:7]
	v_pk_add_f32 v[16:17], v[16:17], v[4:5]
	ds_read_b128 v[4:7], v27
	s_waitcnt lgkmcnt(0)
	v_pk_add_f32 v[14:15], v[14:15], v[6:7]
	v_pk_add_f32 v[12:13], v[12:13], v[4:5]
	ds_read_b128 v[4:7], v28
	s_waitcnt lgkmcnt(0)
	v_pk_add_f32 v[8:9], v[8:9], v[6:7]
	v_pk_add_f32 v[16:17], v[16:17], v[4:5]
	ds_read_b128 v[4:7], v29
	s_waitcnt lgkmcnt(0)
	v_pk_add_f32 v[18:19], v[14:15], v[6:7]
	v_pk_add_f32 v[12:13], v[12:13], v[4:5]
	ds_read_b128 v[4:7], v30
	s_waitcnt lgkmcnt(0)
	v_pk_add_f32 v[14:15], v[8:9], v[6:7]
	v_pk_add_f32 v[16:17], v[16:17], v[4:5]
	ds_read_b128 v[4:7], v31
	v_add_u32_e32 v8, s16, v21
	v_ashrrev_i32_e32 v9, 31, v8
	s_waitcnt lgkmcnt(0)
	v_pk_add_f32 v[4:5], v[12:13], v[4:5]
	v_mov_b64_e32 v[12:13], s[12:13]
	v_mad_i64_i32 v[12:13], s[16:17], v8, s15, v[12:13]
	v_lshlrev_b64 v[8:9], 11, v[8:9]
	v_lshl_add_u64 v[38:39], v[10:11], 2, v[12:13]
	v_lshl_add_u64 v[8:9], s[10:11], 0, v[8:9]
	v_lshlrev_b32_e32 v10, 1, v10
	v_lshl_add_u64 v[8:9], v[8:9], 0, v[10:11]
	global_load_dwordx4 v[34:37], v[8:9], off nt
	v_pk_add_f32 v[6:7], v[18:19], v[6:7]
	s_waitcnt vmcnt(0) lgkmcnt(0)
	v_lshlrev_b32_e32 v40, 16, v34
	v_and_b32_e32 v41, 0xffff0000, v34
	v_lshlrev_b32_e32 v42, 16, v35
	v_and_b32_e32 v43, 0xffff0000, v35
	v_lshlrev_b32_e32 v12, 16, v36
	v_and_b32_e32 v13, 0xffff0000, v36
	v_lshlrev_b32_e32 v18, 16, v37
	v_and_b32_e32 v19, 0xffff0000, v37
	global_load_dwordx4 v[34:37], v[38:39], off nt
	s_waitcnt vmcnt(0) lgkmcnt(0)
	v_pk_fma_f32 v[14:15], v[14:15], v[36:37], v[42:43]
	v_pk_fma_f32 v[16:17], v[16:17], v[34:35], v[40:41]
	global_load_dwordx4 v[34:37], v[38:39], off offset:16 nt
	s_waitcnt vmcnt(0) lgkmcnt(0)
	v_pk_fma_f32 v[18:19], v[6:7], v[36:37], v[18:19]
	v_pk_fma_f32 v[6:7], v[4:5], v[34:35], v[12:13]
	v_cvt_pk_bf16_f32 v4, v16, v17
	v_cvt_pk_bf16_f32 v5, v14, v15
	s_nop 0
	v_cvt_pk_bf16_f32 v6, v6, v7
	v_cvt_pk_bf16_f32 v7, v18, v19
	global_store_dwordx4 v[8:9], v[4:7], off
	s_branch .LBB0_1083

; #define LAS __attribute__((address_space(3)))
; __device__ __forceinline__ f32x4 mfma16(bf16x8 a, bf16x8 b, f32x4 c) { return __builtin_amdgcn_mfma_f32_16x16x32_bf16(a, b, c, 0, 0, 0); }
; template <int RT, class Epi>
; __device__ __forceinline__ void skinny_gemm(const bf16* A, size_t lda, const bf16* Bt, int K, int N, const Epi& epi, int wg, int wg_first, int wg_count, int tid, LAS unsigned char* lds) {
;     ...
;         const bf16* ap = A + (size_t)(r0 + c) * lda + (size_t)w * (K / 8) + 8 * g;
;         const bf16* bp = Bt + (size_t)(n0 + c) * K + (size_t)w * (K / 8) + 8 * g;
; #pragma unroll 4
;         for (int ks = 0; ks < ksteps; ++ks) {
;             bf16x8 af[RT], bfr[2];
; #pragma unroll
;             for (int rt = 0; rt < RT; ++rt) af[rt] = *(const bf16x8*)(ap + (size_t)(16 * rt) * lda + 32 * ks);
;             bfr[0] = *(const bf16x8*)(bp + 32 * ks); bfr[1] = *(const bf16x8*)(bp + (size_t)16 * K + 32 * ks);
; #pragma unroll
;             for (int rt = 0; rt < RT; ++rt) { acc[rt][0] = mfma16(af[rt], bfr[0], acc[rt][0]); acc[rt][1] = mfma16(af[rt], bfr[1], acc[rt][1]); }
;         }
;         LAS float* part = (LAS float*)(lds + w * SK_PART);
; #pragma unroll
;         for (int rt = 0; rt < RT; ++rt)
; #pragma unroll
;             for (int nt = 0; nt < 2; ++nt)
; #pragma unroll
;                 for (int r = 0; r < 4; ++r) part[(16 * rt + 4 * g + r) * 32 + 16 * nt + c] = acc[rt][nt][r];
.LBB0_1204:
	s_and_b32 s14, s9, 64
	v_or_b32_e32 v4, s14, v18
	v_lshlrev_b32_e32 v10, 11, v4
	v_lshl_add_u64 v[6:7], v[0:1], 0, v[10:11]
	v_add_co_u32_e32 v8, vcc, 0x8000, v6
	s_mov_b32 s2, 0x10000
	s_nop 0
	v_addc_co_u32_e32 v9, vcc, 0, v7, vcc
	s_and_b32 s13, s8, 0x7fffffe0
	v_add_co_u32_e32 v12, vcc, s2, v6
	v_or_b32_e32 v10, s13, v18
	s_nop 0
	v_addc_co_u32_e32 v13, vcc, 0, v7, vcc
	s_mov_b32 s2, 0x18000
	v_lshlrev_b64 v[4:5], 11, v[10:11]
	global_load_dwordx4 v[32:35], v[6:7], off nt
	global_load_dwordx4 v[36:39], v[8:9], off nt
	global_load_dwordx4 v[40:43], v[12:13], off nt
	v_add_co_u32_e32 v14, vcc, s2, v6
	v_lshl_add_u64 v[4:5], v[2:3], 0, v[4:5]
	s_nop 0
	v_addc_co_u32_e32 v15, vcc, 0, v7, vcc
	s_mov_b32 s2, 0x8000
	v_add_co_u32_e32 v16, vcc, s2, v4
	global_load_dwordx4 v[44:47], v[14:15], off nt
	global_load_dwordx4 v[48:51], v[4:5], off nt
	v_addc_co_u32_e32 v17, vcc, 0, v5, vcc
	global_load_dwordx4 v[52:55], v[16:17], off nt
	s_waitcnt vmcnt(0) lgkmcnt(0)
	v_mfma_f32_16x16x32_bf16 v[56:59], v[32:35], v[48:51], 0
	v_mfma_f32_16x16x32_bf16 v[32:35], v[32:35], v[52:55], 0
	v_mfma_f32_16x16x32_bf16 v[60:63], v[36:39], v[48:51], 0
	v_mfma_f32_16x16x32_bf16 v[36:39], v[36:39], v[52:55], 0
	v_mfma_f32_16x16x32_bf16 v[64:67], v[40:43], v[48:51], 0
	v_mfma_f32_16x16x32_bf16 v[40:43], v[40:43], v[52:55], 0
	v_mfma_f32_16x16x32_bf16 v[48:51], v[44:47], v[48:51], 0
	v_mfma_f32_16x16x32_bf16 v[44:47], v[44:47], v[52:55], 0
	global_load_dwordx4 v[52:55], v[6:7], off offset:64 nt
	global_load_dwordx4 v[68:71], v[8:9], off offset:64 nt
	global_load_dwordx4 v[72:75], v[12:13], off offset:64 nt
	global_load_dwordx4 v[76:79], v[14:15], off offset:64 nt
	global_load_dwordx4 v[80:83], v[4:5], off offset:64 nt
	global_load_dwordx4 v[84:87], v[16:17], off offset:64 nt
	s_waitcnt vmcnt(0) lgkmcnt(0)
	v_mfma_f32_16x16x32_bf16 v[56:59], v[52:55], v[80:83], v[56:59]
	v_mfma_f32_16x16x32_bf16 v[32:35], v[52:55], v[84:87], v[32:35]
	v_mfma_f32_16x16x32_bf16 v[52:55], v[68:71], v[80:83], v[60:63]
	v_mfma_f32_16x16x32_bf16 v[36:39], v[68:71], v[84:87], v[36:39]
	v_mfma_f32_16x16x32_bf16 v[60:63], v[72:75], v[80:83], v[64:67]
	v_mfma_f32_16x16x32_bf16 v[40:43], v[72:75], v[84:87], v[40:43]
	v_mfma_f32_16x16x32_bf16 v[48:51], v[76:79], v[80:83], v[48:51]
	v_mfma_f32_16x16x32_bf16 v[44:47], v[76:79], v[84:87], v[44:47]
	global_load_dwordx4 v[64:67], v[6:7], off offset:128 nt
	global_load_dwordx4 v[68:71], v[8:9], off offset:128 nt
	global_load_dwordx4 v[72:75], v[12:13], off offset:128 nt
	global_load_dwordx4 v[76:79], v[14:15], off offset:128 nt
	global_load_dwordx4 v[80:83], v[4:5], off offset:128 nt
	global_load_dwordx4 v[84:87], v[16:17], off offset:128 nt
	s_waitcnt vmcnt(0) lgkmcnt(0)
	v_mfma_f32_16x16x32_bf16 v[56:59], v[64:67], v[80:83], v[56:59]
	v_mfma_f32_16x16x32_bf16 v[32:35], v[64:67], v[84:87], v[32:35]
	v_mfma_f32_16x16x32_bf16 v[52:55], v[68:71], v[80:83], v[52:55]
	v_mfma_f32_16x16x32_bf16 v[36:39], v[68:71], v[84:87], v[36:39]
	v_mfma_f32_16x16x32_bf16 v[60:63], v[72:75], v[80:83], v[60:63]
	v_mfma_f32_16x16x32_bf16 v[40:43], v[72:75], v[84:87], v[40:43]
	v_mfma_f32_16x16x32_bf16 v[48:51], v[76:79], v[80:83], v[48:51]
	v_mfma_f32_16x16x32_bf16 v[44:47], v[76:79], v[84:87], v[44:47]
	global_load_dwordx4 v[64:67], v[6:7], off offset:192 nt
	s_nop 0
	global_load_dwordx4 v[6:9], v[8:9], off offset:192 nt
	s_nop 0
	global_load_dwordx4 v[68:71], v[12:13], off offset:192 nt
	s_nop 0
	global_load_dwordx4 v[12:15], v[14:15], off offset:192 nt
	s_nop 0
	global_load_dwordx4 v[72:75], v[4:5], off offset:192 nt
	global_load_dwordx4 v[76:79], v[16:17], off offset:192 nt
	s_waitcnt vmcnt(0) lgkmcnt(0)
	v_mfma_f32_16x16x32_bf16 v[56:59], v[64:67], v[72:75], v[56:59]
	v_mfma_f32_16x16x32_bf16 v[32:35], v[64:67], v[76:79], v[32:35]
	s_nop 7
	ds_write2_b32 v30, v56, v32 offset1:16
	ds_write2_b32 v30, v57, v33 offset0:32 offset1:48
	ds_write2_b32 v30, v58, v34 offset0:64 offset1:80
	ds_write2_b32 v30, v59, v35 offset0:96 offset1:112
	v_mfma_f32_16x16x32_bf16 v[52:55], v[6:9], v[72:75], v[52:55]
	v_mfma_f32_16x16x32_bf16 v[4:7], v[6:9], v[76:79], v[36:39]
	v_add_u32_e32 v8, 0x800, v30
	s_nop 6
	ds_write2_b32 v8, v52, v4 offset1:16
	ds_write2_b32 v8, v53, v5 offset0:32 offset1:48
	ds_write2_b32 v8, v54, v6 offset0:64 offset1:80
	ds_write2_b32 v8, v55, v7 offset0:96 offset1:112
	v_mfma_f32_16x16x32_bf16 v[36:39], v[68:71], v[72:75], v[60:63]
	v_add_u32_e32 v4, 0x1000, v30
	v_mfma_f32_16x16x32_bf16 v[40:43], v[68:71], v[76:79], v[40:43]
	s_nop 7
	ds_write2_b32 v4, v36, v40 offset1:16
	ds_write2_b32 v4, v37, v41 offset0:32 offset1:48
	ds_write2_b32 v4, v38, v42 offset0:64 offset1:80
	ds_write2_b32 v4, v39, v43 offset0:96 offset1:112
	v_mfma_f32_16x16x32_bf16 v[48:51], v[12:15], v[72:75], v[48:51]
	v_add_u32_e32 v4, 0x1800, v30
	v_mfma_f32_16x16x32_bf16 v[12:15], v[12:15], v[76:79], v[44:47]
	s_nop 7
	ds_write2_b32 v4, v48, v12 offset1:16
	ds_write2_b32 v4, v49, v13 offset0:32 offset1:48
	ds_write2_b32 v4, v50, v14 offset0:64 offset1:80
	ds_write2_b32 v4, v51, v15 offset0:96 offset1:112
	s_waitcnt lgkmcnt(0)
	s_barrier
; #define LAS __attribute__((address_space(3)))
; __device__ __forceinline__ void sync_threads() { __syncthreads(); }
; template <int RT, class Epi>
; __device__ __forceinline__ void skinny_gemm(const bf16* A, size_t lda, const bf16* Bt, int K, int N, const Epi& epi, int wg, int wg_first, int wg_count, int tid, LAS unsigned char* lds) {
;     ...
;         sync_threads();
;         if (RT == 8 || tid < 64 * RT) {
;             const int row = tid >> 2, c8 = (tid & 3) * 8;
;             f32x4 v0 = (f32x4){0.f, 0.f, 0.f, 0.f}, v1 = (f32x4){0.f, 0.f, 0.f, 0.f};
; #pragma unroll
;             for (int ww = 0; ww < 8; ++ww) { const LAS float* pp = (const LAS float*)(lds + ww * SK_PART) + row * 32 + c8; v0 = v0 + *(const LAS f32x4*)pp; v1 = v1 + *(const LAS f32x4*)(pp + 4); }
;             epi(r0 + row, n0 + c8, v0, v1);
;         }
;         sync_threads();
;     }
; }
	s_and_saveexec_b64 s[2:3], s[6:7]
	s_cbranch_execz .LBB0_1203
	ds_read_b128 v[4:7], v21
	ds_read_b128 v[12:15], v21 offset:16
	v_or_b32_e32 v10, s13, v20
	v_lshlrev_b32_e32 v10, 1, v10
	s_waitcnt lgkmcnt(1)
	v_pk_add_f32 v[8:9], v[6:7], 0 op_sel_hi:[1,0]
	v_pk_add_f32 v[16:17], v[4:5], 0 op_sel_hi:[1,0]
	ds_read_b128 v[4:7], v21 offset:16384
	s_waitcnt lgkmcnt(1)
	v_pk_add_f32 v[14:15], v[14:15], 0 op_sel_hi:[1,0]
	v_pk_add_f32 v[12:13], v[12:13], 0 op_sel_hi:[1,0]
	s_waitcnt lgkmcnt(0)
	v_pk_add_f32 v[8:9], v[8:9], v[6:7]
	v_pk_add_f32 v[16:17], v[16:17], v[4:5]
	ds_read_b128 v[4:7], v21 offset:16400
	s_waitcnt lgkmcnt(0)
	v_pk_add_f32 v[14:15], v[14:15], v[6:7]
	v_pk_add_f32 v[12:13], v[12:13], v[4:5]
	ds_read_b128 v[4:7], v21 offset:32768
	s_waitcnt lgkmcnt(0)
	v_pk_add_f32 v[8:9], v[8:9], v[6:7]
	v_pk_add_f32 v[16:17], v[16:17], v[4:5]
	ds_read_b128 v[4:7], v21 offset:32784
	s_waitcnt lgkmcnt(0)
	v_pk_add_f32 v[14:15], v[14:15], v[6:7]
	v_pk_add_f32 v[12:13], v[12:13], v[4:5]
	ds_read_b128 v[4:7], v21 offset:49152
	s_waitcnt lgkmcnt(0)
	v_pk_add_f32 v[8:9], v[8:9], v[6:7]
	v_pk_add_f32 v[16:17], v[16:17], v[4:5]
	ds_read_b128 v[4:7], v21 offset:49168
	s_waitcnt lgkmcnt(0)
	v_pk_add_f32 v[14:15], v[14:15], v[6:7]
	v_pk_add_f32 v[12:13], v[12:13], v[4:5]
	ds_read_b128 v[4:7], v22
	s_waitcnt lgkmcnt(0)
	v_pk_add_f32 v[8:9], v[8:9], v[6:7]
	v_pk_add_f32 v[16:17], v[16:17], v[4:5]
	ds_read_b128 v[4:7], v23
	s_waitcnt lgkmcnt(0)
	v_pk_add_f32 v[14:15], v[14:15], v[6:7]
	v_pk_add_f32 v[12:13], v[12:13], v[4:5]
	ds_read_b128 v[4:7], v24
	s_waitcnt lgkmcnt(0)
	v_pk_add_f32 v[8:9], v[8:9], v[6:7]
	v_pk_add_f32 v[16:17], v[16:17], v[4:5]
	ds_read_b128 v[4:7], v25
	s_waitcnt lgkmcnt(0)
	v_pk_add_f32 v[14:15], v[14:15], v[6:7]
	v_pk_add_f32 v[12:13], v[12:13], v[4:5]
	ds_read_b128 v[4:7], v26
	s_waitcnt lgkmcnt(0)
	v_pk_add_f32 v[8:9], v[8:9], v[6:7]
	v_pk_add_f32 v[16:17], v[16:17], v[4:5]
	ds_read_b128 v[4:7], v27
	s_waitcnt lgkmcnt(0)
	v_pk_add_f32 v[14:15], v[14:15], v[6:7]
	v_pk_add_f32 v[12:13], v[12:13], v[4:5]
	ds_read_b128 v[4:7], v28
	s_waitcnt lgkmcnt(0)
	v_pk_add_f32 v[8:9], v[8:9], v[6:7]
	v_pk_add_f32 v[16:17], v[16:17], v[4:5]
	ds_read_b128 v[4:7], v29
	s_waitcnt lgkmcnt(0)
	v_pk_add_f32 v[4:5], v[12:13], v[4:5]
	s_nop 0
	v_max_f32_e32 v4, 0, v4
	v_pk_add_f32 v[6:7], v[14:15], v[6:7]
	v_max_f32_e32 v13, 0, v16
	v_mul_f32_e32 v14, v4, v4
	v_max_f32_e32 v4, 0, v17
	v_add_u32_e32 v12, s14, v19
	v_mul_f32_e32 v13, v13, v13
	v_max_f32_e32 v5, 0, v5
	v_mul_f32_e32 v4, v4, v4
	v_max_f32_e32 v6, 0, v6
	v_max_f32_e32 v7, 0, v7
	v_mul_f32_e32 v15, v5, v5
	v_max_f32_e32 v5, 0, v8
	v_mul_f32_e32 v8, v6, v6
	v_mul_f32_e32 v7, v7, v7
	v_cvt_pk_bf16_f32 v4, v13, v4
	v_ashrrev_i32_e32 v13, 31, v12
	v_max_f32_e32 v6, 0, v9
	v_cvt_pk_bf16_f32 v7, v8, v7
	v_lshlrev_b64 v[8:9], 13, v[12:13]
	v_lshl_add_u64 v[8:9], s[10:11], 0, v[8:9]
	v_mul_f32_e32 v5, v5, v5
	v_mul_f32_e32 v6, v6, v6
	v_lshl_add_u64 v[8:9], v[8:9], 0, v[10:11]
	v_cvt_pk_bf16_f32 v5, v5, v6
	v_cvt_pk_bf16_f32 v6, v14, v15
	global_store_dwordx4 v[8:9], v[4:7], off
	s_branch .LBB0_1203

; #define LAS __attribute__((address_space(3)))
; __device__ __forceinline__ f32x4 mfma16(bf16x8 a, bf16x8 b, f32x4 c) { return __builtin_amdgcn_mfma_f32_16x16x32_bf16(a, b, c, 0, 0, 0); }
; __device__ __forceinline__ void sync_threads() { __syncthreads(); }
; template <int RT, class Epi>
; __device__ __forceinline__ void skinny_gemm(const bf16* A, size_t lda, const bf16* Bt, int K, int N, const Epi& epi, int wg, int wg_first, int wg_count, int tid, LAS unsigned char* lds) {
;     ...
;         const bf16* ap = A + (size_t)(r0 + c) * lda + (size_t)w * (K / 8) + 8 * g;
;         const bf16* bp = Bt + (size_t)(n0 + c) * K + (size_t)w * (K / 8) + 8 * g;
; #pragma unroll 4
;         for (int ks = 0; ks < ksteps; ++ks) {
;             bf16x8 af[RT], bfr[2];
; #pragma unroll
;             for (int rt = 0; rt < RT; ++rt) af[rt] = *(const bf16x8*)(ap + (size_t)(16 * rt) * lda + 32 * ks);
;             bfr[0] = *(const bf16x8*)(bp + 32 * ks); bfr[1] = *(const bf16x8*)(bp + (size_t)16 * K + 32 * ks);
; #pragma unroll
;             for (int rt = 0; rt < RT; ++rt) { acc[rt][0] = mfma16(af[rt], bfr[0], acc[rt][0]); acc[rt][1] = mfma16(af[rt], bfr[1], acc[rt][1]); }
;         }
;         LAS float* part = (LAS float*)(lds + w * SK_PART);
; #pragma unroll
;         for (int rt = 0; rt < RT; ++rt)
; #pragma unroll
;             for (int nt = 0; nt < 2; ++nt)
; #pragma unroll
;                 for (int r = 0; r < 4; ++r) part[(16 * rt + 4 * g + r) * 32 + 16 * nt + c] = acc[rt][nt][r];
;         sync_threads();
;         if (RT == 8 || tid < 64 * RT) {
;             const int row = tid >> 2, c8 = (tid & 3) * 8;
;             f32x4 v0 = (f32x4){0.f, 0.f, 0.f, 0.f}, v1 = (f32x4){0.f, 0.f, 0.f, 0.f};
; #pragma unroll
;             for (int ww = 0; ww < 8; ++ww) { const LAS float* pp = (const LAS float*)(lds + ww * SK_PART) + row * 32 + c8; v0 = v0 + *(const LAS f32x4*)pp; v1 = v1 + *(const LAS f32x4*)(pp + 4); }
;             epi(r0 + row, n0 + c8, v0, v1);
;         }
.LBB0_1275:
	v_lshl_add_u64 v[18:19], v[14:15], 0, s[2:3]
	v_add_co_u32_e32 v18, vcc, 0x44900000, v18
	v_lshl_add_u64 v[42:43], v[16:17], 0, s[2:3]
	s_nop 0
	v_addc_co_u32_e32 v19, vcc, 0, v19, vcc
	global_load_dwordx4 v[34:37], v[18:19], off nt
	v_add_co_u32_e32 v46, vcc, 0x7880000, v42
	s_add_u32 s2, s2, 0x100
	s_nop 0
	v_addc_co_u32_e32 v47, vcc, 0, v43, vcc
	v_add_co_u32_e32 v48, vcc, 0x78a0000, v42
	global_load_dwordx4 v[38:41], v[46:47], off nt
	s_nop 0
	v_addc_co_u32_e32 v49, vcc, 0, v43, vcc
	global_load_dwordx4 v[42:45], v[48:49], off nt
	s_addc_u32 s3, s3, 0
	s_cmpk_eq_i32 s2, 0x400
	s_waitcnt vmcnt(0) lgkmcnt(0)
	v_mfma_f32_16x16x32_bf16 v[0:3], v[34:37], v[38:41], v[0:3]
	v_mfma_f32_16x16x32_bf16 v[4:7], v[34:37], v[42:45], v[4:7]
	global_load_dwordx4 v[34:37], v[18:19], off offset:64 nt
	global_load_dwordx4 v[38:41], v[46:47], off offset:64 nt
	global_load_dwordx4 v[42:45], v[48:49], off offset:64 nt
	s_waitcnt vmcnt(0) lgkmcnt(0)
	v_mfma_f32_16x16x32_bf16 v[0:3], v[34:37], v[38:41], v[0:3]
	v_mfma_f32_16x16x32_bf16 v[4:7], v[34:37], v[42:45], v[4:7]
	global_load_dwordx4 v[34:37], v[18:19], off offset:128 nt
	global_load_dwordx4 v[38:41], v[46:47], off offset:128 nt
	global_load_dwordx4 v[42:45], v[48:49], off offset:128 nt
	s_waitcnt vmcnt(0) lgkmcnt(0)
	v_mfma_f32_16x16x32_bf16 v[0:3], v[34:37], v[38:41], v[0:3]
	v_mfma_f32_16x16x32_bf16 v[4:7], v[34:37], v[42:45], v[4:7]
	global_load_dwordx4 v[34:37], v[18:19], off offset:192 nt
	global_load_dwordx4 v[38:41], v[46:47], off offset:192 nt
	global_load_dwordx4 v[42:45], v[48:49], off offset:192 nt
	s_waitcnt vmcnt(0) lgkmcnt(0)
	v_mfma_f32_16x16x32_bf16 v[0:3], v[34:37], v[38:41], v[0:3]
	v_mfma_f32_16x16x32_bf16 v[4:7], v[34:37], v[42:45], v[4:7]
	s_cbranch_scc0 .LBB0_1275
	s_nop 6
	ds_write2_b32 v33, v0, v4 offset1:16
	ds_write2_b32 v33, v1, v5 offset0:32 offset1:48
	ds_write2_b32 v33, v2, v6 offset0:64 offset1:80
	ds_write2_b32 v33, v3, v7 offset0:96 offset1:112
	s_waitcnt lgkmcnt(0)
	s_barrier
	s_and_saveexec_b64 s[2:3], s[0:1]
	s_cbranch_execz .LBB0_1273
	ds_read_b128 v[0:3], v23
	ds_read_b128 v[4:7], v23 offset:16
	s_lshl_b32 s12, s10, 4
	s_lshl_b32 s11, s10, 2
	s_and_b32 s12, s12, 0x70
	s_waitcnt lgkmcnt(1)
	v_pk_add_f32 v[14:15], v[2:3], 0 op_sel_hi:[1,0]
	v_pk_add_f32 v[16:17], v[0:1], 0 op_sel_hi:[1,0]
	ds_read_b128 v[0:3], v23 offset:16384
	s_waitcnt lgkmcnt(1)
	v_pk_add_f32 v[6:7], v[6:7], 0 op_sel_hi:[1,0]
	v_pk_add_f32 v[4:5], v[4:5], 0 op_sel_hi:[1,0]
	s_and_b32 s11, s11, 0x7fffffe0
	v_or_b32_e32 v10, s11, v22
	s_waitcnt lgkmcnt(0)
	v_pk_add_f32 v[14:15], v[14:15], v[2:3]
	v_pk_add_f32 v[16:17], v[16:17], v[0:1]
	ds_read_b128 v[0:3], v23 offset:16400
	s_mov_b32 s11, 0x18000
	s_waitcnt lgkmcnt(0)
	v_pk_add_f32 v[6:7], v[6:7], v[2:3]
	v_pk_add_f32 v[4:5], v[4:5], v[0:1]
	ds_read_b128 v[0:3], v23 offset:32768
	s_waitcnt lgkmcnt(0)
	v_pk_add_f32 v[14:15], v[14:15], v[2:3]
	v_pk_add_f32 v[16:17], v[16:17], v[0:1]
	ds_read_b128 v[0:3], v23 offset:32784
	s_waitcnt lgkmcnt(0)
	v_pk_add_f32 v[6:7], v[6:7], v[2:3]
	v_pk_add_f32 v[4:5], v[4:5], v[0:1]
	ds_read_b128 v[0:3], v23 offset:49152
	s_waitcnt lgkmcnt(0)
	v_pk_add_f32 v[14:15], v[14:15], v[2:3]
	v_pk_add_f32 v[16:17], v[16:17], v[0:1]
	ds_read_b128 v[0:3], v23 offset:49168
	s_waitcnt lgkmcnt(0)
	v_pk_add_f32 v[6:7], v[6:7], v[2:3]
	v_pk_add_f32 v[4:5], v[4:5], v[0:1]
	ds_read_b128 v[0:3], v24
	s_waitcnt lgkmcnt(0)
	v_pk_add_f32 v[14:15], v[14:15], v[2:3]
	v_pk_add_f32 v[16:17], v[16:17], v[0:1]
	ds_read_b128 v[0:3], v25
	s_waitcnt lgkmcnt(0)
	v_pk_add_f32 v[6:7], v[6:7], v[2:3]
	v_pk_add_f32 v[4:5], v[4:5], v[0:1]
	ds_read_b128 v[0:3], v26
	s_waitcnt lgkmcnt(0)
	v_pk_add_f32 v[14:15], v[14:15], v[2:3]
	v_pk_add_f32 v[16:17], v[16:17], v[0:1]
	ds_read_b128 v[0:3], v27
	s_waitcnt lgkmcnt(0)
	v_pk_add_f32 v[6:7], v[6:7], v[2:3]
	v_pk_add_f32 v[4:5], v[4:5], v[0:1]
	ds_read_b128 v[0:3], v28
	s_waitcnt lgkmcnt(0)
	v_pk_add_f32 v[14:15], v[14:15], v[2:3]
	v_pk_add_f32 v[16:17], v[16:17], v[0:1]
	ds_read_b128 v[0:3], v29
	s_waitcnt lgkmcnt(0)
	v_pk_add_f32 v[6:7], v[6:7], v[2:3]
	v_pk_add_f32 v[4:5], v[4:5], v[0:1]
	ds_read_b128 v[0:3], v30
	s_waitcnt lgkmcnt(0)
	v_pk_add_f32 v[14:15], v[14:15], v[2:3]
	v_pk_add_f32 v[16:17], v[16:17], v[0:1]
	ds_read_b128 v[0:3], v31
	s_waitcnt lgkmcnt(0)
	v_pk_add_f32 v[0:1], v[4:5], v[0:1]
	v_add_u32_e32 v4, s12, v21
	v_pk_add_f32 v[2:3], v[6:7], v[2:3]
	v_ashrrev_i32_e32 v5, 31, v4
	v_mov_b64_e32 v[6:7], s[6:7]
	v_mad_i64_i32 v[6:7], s[12:13], v4, s11, v[6:7]
	v_lshlrev_b64 v[4:5], 11, v[4:5]
	v_lshl_add_u64 v[38:39], v[10:11], 2, v[6:7]
	v_lshl_add_u64 v[4:5], s[4:5], 0, v[4:5]
	v_lshlrev_b32_e32 v10, 1, v10
	v_lshl_add_u64 v[4:5], v[4:5], 0, v[10:11]
	global_load_dwordx4 v[34:37], v[4:5], off nt
	s_waitcnt vmcnt(0) lgkmcnt(0)
	v_lshlrev_b32_e32 v40, 16, v34
	v_and_b32_e32 v41, 0xffff0000, v34
	v_lshlrev_b32_e32 v42, 16, v35
	v_and_b32_e32 v43, 0xffff0000, v35
	v_lshlrev_b32_e32 v6, 16, v36
	v_and_b32_e32 v7, 0xffff0000, v36
	v_lshlrev_b32_e32 v18, 16, v37
	v_and_b32_e32 v19, 0xffff0000, v37
	global_load_dwordx4 v[34:37], v[38:39], off nt
	s_waitcnt vmcnt(0) lgkmcnt(0)
	v_pk_fma_f32 v[14:15], v[14:15], v[36:37], v[42:43]
	v_pk_fma_f32 v[16:17], v[16:17], v[34:35], v[40:41]
	global_load_dwordx4 v[34:37], v[38:39], off offset:16 nt
	s_waitcnt vmcnt(0) lgkmcnt(0)
	v_pk_fma_f32 v[18:19], v[2:3], v[36:37], v[18:19]
	v_pk_fma_f32 v[2:3], v[0:1], v[34:35], v[6:7]
	v_cvt_pk_bf16_f32 v0, v16, v17
	v_cvt_pk_bf16_f32 v1, v14, v15
	s_nop 0
	v_cvt_pk_bf16_f32 v2, v2, v3
	v_cvt_pk_bf16_f32 v3, v18, v19
	global_store_dwordx4 v[4:5], v[0:3], off
	s_branch .LBB0_1273
